# speedup vs baseline: 1.0140x; 1.0052x over previous
; __device__ void attn_item(const Params& p, int l, int b, int h, int qb, char* smem) {
;     const int tid = opaque_tid(), lane = tid & 63, w = tid >> 6;
;     const int r = lane & 15, g4 = lane >> 4;
;     char* Ks = smem; char* Vt = smem + 16384; float* ckl = (float*)(smem + 32768);
;     const int q0 = qb * 128;
;     const int nkeys = q0 + 128;
;     const int nkt = nkeys >> 6;
;     const int bh = b * 16 + h;
;     uint2 gpre[2][4];
; #pragma unroll
;     for (int qt = 0; qt < 2; ++qt)
; #pragma unroll
;         for (int dt = 0; dt < 4; ++dt)
;             gpre[qt][dt] = *(const uint2*)(p.gb + (size_t)(b * 2048 + q0 + 32 * w + 16 * qt + r) * 1024 + h * 64 + 16 * dt + 4 * g4);
;     bf16x8 qf[2][2];
; #pragma unroll
;     for (int qt = 0; qt < 2; ++qt)
; #pragma unroll
;         for (int ks = 0; ks < 2; ++ks)
;             qf[qt][ks] = *(const bf16x8*)(p.qb + (size_t)(b * 2048 + q0 + 32 * w + 16 * qt + r) * 1024 + h * 64 + ks * 32 + g4 * 8);
;     f32x4 o[4][2];
; #pragma unroll
;     for (int dt = 0; dt < 4; ++dt)
; #pragma unroll
;         for (int qt = 0; qt < 2; ++qt) o[dt][qt] = (f32x4){0.f, 0.f, 0.f, 0.f};
;     float mrun[2] = {-INFINITY, -INFINITY}, lrun[2] = {0.f, 0.f};
;     const int lrow = tid >> 3, lkc = tid & 7;
;     const u16* kp = p.kb + (size_t)(b * 2048 + lrow) * 1024 + h * 64 + lkc * 8;
;     const u16* vp = p.vT + ((size_t)(bh * 64 + lrow)) * 2048 + lkc * 8;
;     const int lds_w = lrow * 128 + ((lkc ^ (lrow & 7)) << 4);
;     uint4 rk0, rk1, rv0, rv1;
;     ...
;     AL(nkt - 1);
;     {
;         float tot[16];
;         const float4* ct = (const float4*)(p.ctot + bh * 16);
; #pragma unroll
;         for (int i = 0; i < 4; ++i) { float4 v = ct[i]; tot[4 * i] = v.x; tot[4 * i + 1] = v.y; tot[4 * i + 2] = v.z; tot[4 * i + 3] = v.w; }
;         const int half = tid >> 7, tl = tid & 127;
;         float base = half ? tot[0] : 0.f;
; #pragma unroll
;         for (int jj = 0; jj < 8; ++jj) {
;             const int tile = 2 * jj + half;
;             if (tile <= qb) ckl[tile * 128 + tl] = (base + p.clT[(size_t)bh * 2048 + tile * 128 + tl]) * LOG2E;
;             base += tot[2 * jj + half] + tot[(2 * jj + half + 1) & 15];
;         }
;     }
;     ...
;     const float s_bound = sqrtf(fmaxf(fmaxf(red[0], red[1]), fmaxf(red[2], red[3]))) * __uint_as_float(p.knmax[l * 256 + bh]) * sl2 * 1.02f;
.LBB0_466:
	s_or_b64 exec, exec, s[0:1]
	s_cmpk_gt_i32 s52, 0x7f
	s_cbranch_scc0 .LBB0_521
	s_cmpk_gt_u32 s52, 0x37f
	s_cbranch_scc0 .LBB0_522
	s_add_i32 s0, s52, 0xfffffc80
	s_lshr_b32 s4, s0, 8
	s_sub_i32 s6, 15, s4
	s_bfe_u32 s0, s0, 0x40004
	v_mov_b32_e32 v54, v141
	s_lshl_b32 s5, s6, 7
	s_lshl_b32 s10, s0, 11
	s_lshl_b32 s7, s0, 4
	v_ashrrev_i32_e32 v58, 6, v54
	v_and_b32_e32 v55, 15, v54
	s_or_b32 s0, s5, s10
	v_lshlrev_b32_e32 v57, 5, v58
	v_or_b32_e32 v0, s0, v55
	s_and_b32 s8, s52, 15
	v_add_u32_e32 v2, v0, v57
	v_readlane_b32 s12, v214, 50
	s_lshl_b32 s2, s8, 7
	v_readlane_b32 s20, v214, 58
	v_ashrrev_i32_e32 v3, 31, v2
	v_bfe_u32 v56, v54, 4, 2
	v_readlane_b32 s21, v214, 59
	s_add_u32 s0, s20, s2
	v_lshlrev_b64 v[126:127], 11, v[2:3]
	v_or_b32_e32 v2, 16, v2
	s_addc_u32 s1, s21, 0
	v_lshlrev_b32_e32 v0, 3, v56
	v_ashrrev_i32_e32 v3, 31, v2
	v_readlane_b32 s14, v214, 52
	v_lshl_add_u64 v[4:5], s[0:1], 0, v[0:1]
	v_lshlrev_b64 v[116:117], 11, v[2:3]
	v_readlane_b32 s15, v214, 53
	v_lshl_add_u64 v[6:7], v[4:5], 0, v[126:127]
	v_lshl_add_u64 v[2:3], v[4:5], 0, v[116:117]
	s_add_u32 s0, s14, s2
	global_load_dwordx2 v[128:129], v[6:7], off
	global_load_dwordx2 v[124:125], v[6:7], off offset:32
	global_load_dwordx2 v[122:123], v[6:7], off offset:64
	global_load_dwordx2 v[120:121], v[6:7], off offset:96
	global_load_dwordx2 v[118:119], v[2:3], off
	global_load_dwordx2 v[114:115], v[2:3], off offset:32
	global_load_dwordx2 v[112:113], v[2:3], off offset:64
	global_load_dwordx2 v[110:111], v[2:3], off offset:96
	s_addc_u32 s1, s15, 0
	v_and_b32_e32 v2, 48, v54
	v_mov_b32_e32 v3, v1
	v_lshl_add_u64 v[2:3], s[0:1], 0, v[2:3]
	v_lshl_add_u64 v[8:9], v[2:3], 0, v[126:127]
	v_lshl_add_u64 v[2:3], v[2:3], 0, v[116:117]
	v_ashrrev_i32_e32 v59, 3, v54
	global_load_dwordx4 v[4:7], v[8:9], off
	s_nop 0
	global_load_dwordx4 v[8:11], v[8:9], off offset:64
	s_nop 0
	global_load_dwordx4 v[12:15], v[2:3], off
	global_load_dwordx4 v[16:19], v[2:3], off offset:64
	v_add_u32_e32 v2, s10, v59
	v_ashrrev_i32_e32 v3, 31, v2
	v_readlane_b32 s16, v214, 54
	v_readlane_b32 s17, v214, 55
	v_lshlrev_b64 v[2:3], 11, v[2:3]
	s_or_b32 s9, s7, s8
	v_lshl_add_u64 v[2:3], s[16:17], 0, v[2:3]
	v_lshlrev_b32_e32 v20, 4, v54
	v_lshl_add_u64 v[2:3], v[2:3], 0, s[2:3]
	v_and_b32_e32 v20, 0x70, v20
	v_mov_b32_e32 v21, v1
	s_lshl_b32 s0, s9, 6
	v_lshl_add_u64 v[130:131], v[2:3], 0, v[20:21]
	v_add_u32_e32 v2, s0, v59
	v_ashrrev_i32_e32 v3, 31, v2
	v_readlane_b32 s18, v214, 56
	v_readlane_b32 s19, v214, 57
	v_lshlrev_b64 v[2:3], 12, v[2:3]
	s_or_b32 s1, s5, 64
	v_lshl_add_u64 v[2:3], s[18:19], 0, v[2:3]
	s_lshl_b32 s2, s1, 11
	v_lshl_add_u64 v[132:133], v[2:3], 0, v[20:21]
	v_lshl_add_u64 v[2:3], v[130:131], 0, s[2:3]
	s_lshl_b32 s2, s6, 18
	s_or_b32 s2, s2, 0x30000
	v_readlane_b32 s13, v214, 51
	v_readlane_b32 s22, v214, 60
	v_readlane_b32 s23, v214, 61
	v_readlane_b32 s24, v214, 62
	v_readlane_b32 s25, v214, 63
	v_readlane_b32 s26, v213, 0
	v_readlane_b32 s27, v213, 1
	v_lshl_add_u64 v[24:25], v[130:131], 0, s[2:3]
	s_lshl_b32 s2, s1, 1
	v_mov_b32_e32 v28, s0
	s_mov_b64 s[0:1], 0x20000
	v_readlane_b32 s12, v213, 4
	v_lshl_add_u64 v[134:135], v[132:133], 0, s[0:1]
	v_readlane_b32 s18, v213, 10
	v_readlane_b32 s19, v213, 11
	v_lshl_add_u64 v[32:33], v[134:135], 0, s[2:3]
	global_load_dwordx4 v[20:23], v[2:3], off
	s_nop 0
	global_load_dwordx4 v[24:27], v[24:25], off
	s_nop 0
	global_load_dwordx4 v[44:47], v28, s[18:19] offset:16
	global_load_dwordx4 v[48:51], v28, s[18:19]
	v_lshl_add_u64 v[2:3], v[132:133], 0, s[2:3]
	global_load_dwordx4 v[36:39], v28, s[18:19] offset:48
	global_load_dwordx4 v[40:43], v28, s[18:19] offset:32
	s_nop 0
	global_load_dwordx4 v[28:31], v[2:3], off
	s_nop 0
	global_load_dwordx4 v[32:35], v[32:33], off
	s_movk_i32 s0, 0x7f
	v_readlane_b32 s16, v213, 8
	v_cmp_lt_u32_e32 vcc, s0, v54
	s_lshl_b32 s0, s9, 13
	v_readlane_b32 s17, v213, 9
	v_lshlrev_b32_e32 v2, 2, v54
	s_add_u32 s0, s16, s0
	v_ashrrev_i32_e32 v60, 7, v54
	v_and_b32_e32 v2, 0x1fc, v2
	s_addc_u32 s1, s17, 0
	v_mov_b32_e32 v3, v1
	v_lshl_add_u64 v[52:53], s[0:1], 0, v[2:3]
	v_readlane_b32 s13, v213, 5
	v_readlane_b32 s14, v213, 6
	v_readlane_b32 s15, v213, 7
	v_readlane_b32 s20, v213, 12
	v_readlane_b32 s21, v213, 13
	v_readlane_b32 s22, v213, 14
	v_readlane_b32 s23, v213, 15
	v_readlane_b32 s24, v213, 16
	v_readlane_b32 s25, v213, 17
	v_readlane_b32 s26, v213, 18
	v_readlane_b32 s27, v213, 19
	s_waitcnt vmcnt(4)
	v_cndmask_b32_e32 v61, 0, v48, vcc
	v_cmp_ge_i32_e32 vcc, s6, v60
	s_and_saveexec_b64 s[0:1], vcc
	s_cbranch_execz .LBB0_470
	v_and_b32_e32 v62, 0xffffff80, v54
	v_ashrrev_i32_e32 v63, 31, v62
	v_lshl_add_u64 v[64:65], v[62:63], 2, v[52:53]
	global_load_dword v216, v[64:65], off
	global_load_dword v217, v[64:65], off offset:1024
	global_load_dword v218, v[64:65], off offset:2048
	global_load_dword v219, v[64:65], off offset:3072
	v_add_co_u32_e32 v224, vcc, 0x1000, v64
	s_nop 1
	v_addc_co_u32_e32 v225, vcc, 0, v65, vcc
	global_load_dword v220, v[224:225], off
	global_load_dword v221, v[224:225], off offset:1024
	global_load_dword v222, v[224:225], off offset:2048
	global_load_dword v223, v[224:225], off offset:3072
	v_lshl_or_b32 v62, v62, 2, v2
	s_waitcnt vmcnt(0)
	v_mov_b32_e32 v3, v216
	v_add_f32_e32 v3, v61, v3
	v_mul_f32_e32 v3, 0x3fb8aa3b, v3
	ds_write_b32 v62, v3 offset:32768
; __device__ void attn_item(const Params& p, int l, int b, int h, int qb, char* smem) {
;     ...
;         const int half = tid >> 7, tl = tid & 127;
;         float base = half ? tot[0] : 0.f;
; #pragma unroll
;         for (int jj = 0; jj < 8; ++jj) {
;             const int tile = 2 * jj + half;
;             if (tile <= qb) ckl[tile * 128 + tl] = (base + p.clT[(size_t)bh * 2048 + tile * 128 + tl]) * LOG2E;
;             base += tot[2 * jj + half] + tot[(2 * jj + half + 1) & 15];
;         }
.LBB0_470:
	s_or_b64 exec, exec, s[0:1]
	v_cmp_eq_u32_e32 vcc, 1, v60
	v_add_u32_e32 v62, 1, v60
	v_and_b32_e32 v62, 15, v62
	v_cndmask_b32_e32 v3, v48, v49, vcc
	v_cmp_eq_u32_e32 vcc, 2, v60
	s_nop 1
	v_cndmask_b32_e32 v3, v3, v50, vcc
	v_cmp_eq_u32_e32 vcc, 3, v60
	s_nop 1
	v_cndmask_b32_e32 v3, v3, v51, vcc
	v_cmp_eq_u32_e32 vcc, 4, v60
	s_nop 1
	v_cndmask_b32_e32 v3, v3, v44, vcc
	v_cmp_eq_u32_e32 vcc, 5, v60
	s_nop 1
	v_cndmask_b32_e32 v3, v3, v45, vcc
	v_cmp_eq_u32_e32 vcc, 6, v60
	s_nop 1
	v_cndmask_b32_e32 v3, v3, v46, vcc
	v_cmp_eq_u32_e32 vcc, 7, v60
	s_nop 1
	v_cndmask_b32_e32 v3, v3, v47, vcc
	v_cmp_eq_u32_e32 vcc, 8, v60
	s_waitcnt vmcnt(2)
	s_nop 0
	v_cndmask_b32_e32 v3, v3, v40, vcc
	v_cmp_eq_u32_e32 vcc, 9, v60
	s_nop 1
	v_cndmask_b32_e32 v3, v3, v41, vcc
	v_cmp_eq_u32_e32 vcc, 10, v60
	s_nop 1
	v_cndmask_b32_e32 v3, v3, v42, vcc
	v_cmp_eq_u32_e32 vcc, 11, v60
	s_nop 1
	v_cndmask_b32_e32 v3, v3, v43, vcc
	v_cmp_eq_u32_e32 vcc, 12, v60
	s_nop 1
	v_cndmask_b32_e32 v3, v3, v36, vcc
	v_cmp_eq_u32_e32 vcc, 13, v60
	s_nop 1
	v_cndmask_b32_e32 v3, v3, v37, vcc
	v_cmp_eq_u32_e32 vcc, 14, v60
	s_nop 1
	v_cndmask_b32_e32 v3, v3, v38, vcc
	v_cmp_eq_u32_e32 vcc, 15, v60
	s_nop 1
	v_cndmask_b32_e32 v3, v3, v39, vcc
	v_cmp_eq_u32_e32 vcc, 1, v62
	s_nop 1
	v_cndmask_b32_e32 v63, v48, v49, vcc
	v_cmp_eq_u32_e32 vcc, 2, v62
	s_nop 1
	v_cndmask_b32_e32 v63, v63, v50, vcc
	v_cmp_eq_u32_e32 vcc, 3, v62
	s_nop 1
	v_cndmask_b32_e32 v63, v63, v51, vcc
	v_cmp_eq_u32_e32 vcc, 4, v62
	s_nop 1
	v_cndmask_b32_e32 v63, v63, v44, vcc
	v_cmp_eq_u32_e32 vcc, 5, v62
	s_nop 1
	v_cndmask_b32_e32 v63, v63, v45, vcc
	v_cmp_eq_u32_e32 vcc, 6, v62
	s_nop 1
	v_cndmask_b32_e32 v63, v63, v46, vcc
	v_cmp_eq_u32_e32 vcc, 7, v62
	s_nop 1
	v_cndmask_b32_e32 v63, v63, v47, vcc
	v_cmp_eq_u32_e32 vcc, 8, v62
	s_nop 1
	v_cndmask_b32_e32 v63, v63, v40, vcc
	v_cmp_eq_u32_e32 vcc, 9, v62
	s_nop 1
	v_cndmask_b32_e32 v63, v63, v41, vcc
	v_cmp_eq_u32_e32 vcc, 10, v62
	s_nop 1
	v_cndmask_b32_e32 v63, v63, v42, vcc
	v_cmp_eq_u32_e32 vcc, 11, v62
	s_nop 1
	v_cndmask_b32_e32 v63, v63, v43, vcc
	v_cmp_eq_u32_e32 vcc, 12, v62
	s_nop 1
	v_cndmask_b32_e32 v63, v63, v36, vcc
	v_cmp_eq_u32_e32 vcc, 13, v62
	s_nop 1
	v_cndmask_b32_e32 v63, v63, v37, vcc
	v_cmp_eq_u32_e32 vcc, 14, v62
	s_nop 1
	v_cndmask_b32_e32 v63, v63, v38, vcc
	v_cmp_eq_u32_e32 vcc, 15, v62
	s_nop 1
	v_cndmask_b32_e32 v62, v63, v39, vcc
	v_add_f32_e32 v3, v3, v62
	v_add_f32_e32 v3, v61, v3
	v_add_u32_e32 v61, 2, v60
	v_cmp_ge_i32_e32 vcc, s6, v61
	s_and_saveexec_b64 s[0:1], vcc
	s_cbranch_execz .LBB0_472
	v_lshlrev_b32_e32 v62, 7, v61
	v_ashrrev_i32_e32 v63, 31, v62
	v_lshl_add_u64 v[62:63], v[62:63], 2, v[52:53]
	v_mov_b32_e32 v62, v217
	v_lshl_or_b32 v63, v61, 9, v2
	s_waitcnt vmcnt(0)
	v_add_f32_e32 v62, v3, v62
	v_mul_f32_e32 v62, 0x3fb8aa3b, v62
	ds_write_b32 v63, v62 offset:32768
.LBB0_472:
	s_or_b64 exec, exec, s[0:1]
	v_cmp_eq_u32_e32 vcc, 1, v61
	s_nop 1
	v_cndmask_b32_e32 v62, v48, v49, vcc
	v_cmp_eq_u32_e32 vcc, 2, v61
	s_nop 1
	v_cndmask_b32_e32 v62, v62, v50, vcc
	v_cmp_eq_u32_e32 vcc, 3, v61
	s_nop 1
	v_cndmask_b32_e32 v62, v62, v51, vcc
	v_cmp_eq_u32_e32 vcc, 4, v61
	s_nop 1
	v_cndmask_b32_e32 v62, v62, v44, vcc
	v_cmp_eq_u32_e32 vcc, 5, v61
	s_nop 1
	v_cndmask_b32_e32 v62, v62, v45, vcc
	v_cmp_eq_u32_e32 vcc, 6, v61
	s_nop 1
	v_cndmask_b32_e32 v62, v62, v46, vcc
	v_cmp_eq_u32_e32 vcc, 7, v61
	s_nop 1
	v_cndmask_b32_e32 v62, v62, v47, vcc
	v_cmp_eq_u32_e32 vcc, 8, v61
	s_nop 1
	v_cndmask_b32_e32 v62, v62, v40, vcc
	v_cmp_eq_u32_e32 vcc, 9, v61
	s_nop 1
	v_cndmask_b32_e32 v62, v62, v41, vcc
	v_cmp_eq_u32_e32 vcc, 10, v61
	s_nop 1
	v_cndmask_b32_e32 v62, v62, v42, vcc
	v_cmp_eq_u32_e32 vcc, 11, v61
	s_nop 1
	v_cndmask_b32_e32 v62, v62, v43, vcc
	v_cmp_eq_u32_e32 vcc, 12, v61
	s_nop 1
	v_cndmask_b32_e32 v62, v62, v36, vcc
	v_cmp_eq_u32_e32 vcc, 13, v61
	s_nop 1
	v_cndmask_b32_e32 v62, v62, v37, vcc
	v_cmp_eq_u32_e32 vcc, 14, v61
	s_nop 1
	v_cndmask_b32_e32 v62, v62, v38, vcc
	v_cmp_eq_u32_e32 vcc, 15, v61
	s_nop 1
	v_cndmask_b32_e32 v61, v62, v39, vcc
	v_add_u32_e32 v62, 3, v60
	v_and_b32_e32 v62, 15, v62
	v_cmp_eq_u32_e32 vcc, 1, v62
	s_nop 1
	v_cndmask_b32_e32 v63, v48, v49, vcc
	v_cmp_eq_u32_e32 vcc, 2, v62
	s_nop 1
	v_cndmask_b32_e32 v63, v63, v50, vcc
	v_cmp_eq_u32_e32 vcc, 3, v62
	s_nop 1
	v_cndmask_b32_e32 v63, v63, v51, vcc
	v_cmp_eq_u32_e32 vcc, 4, v62
	s_nop 1
	v_cndmask_b32_e32 v63, v63, v44, vcc
	v_cmp_eq_u32_e32 vcc, 5, v62
	s_nop 1
	v_cndmask_b32_e32 v63, v63, v45, vcc
	v_cmp_eq_u32_e32 vcc, 6, v62
	s_nop 1
	v_cndmask_b32_e32 v63, v63, v46, vcc
	v_cmp_eq_u32_e32 vcc, 7, v62
	s_nop 1
	v_cndmask_b32_e32 v63, v63, v47, vcc
	v_cmp_eq_u32_e32 vcc, 8, v62
	s_nop 1
	v_cndmask_b32_e32 v63, v63, v40, vcc
	v_cmp_eq_u32_e32 vcc, 9, v62
	s_nop 1
	v_cndmask_b32_e32 v63, v63, v41, vcc
	v_cmp_eq_u32_e32 vcc, 10, v62
	s_nop 1
	v_cndmask_b32_e32 v63, v63, v42, vcc
	v_cmp_eq_u32_e32 vcc, 11, v62
	s_nop 1
	v_cndmask_b32_e32 v63, v63, v43, vcc
	v_cmp_eq_u32_e32 vcc, 12, v62
	s_nop 1
	v_cndmask_b32_e32 v63, v63, v36, vcc
	v_cmp_eq_u32_e32 vcc, 13, v62
	s_nop 1
	v_cndmask_b32_e32 v63, v63, v37, vcc
	v_cmp_eq_u32_e32 vcc, 14, v62
	s_nop 1
	v_cndmask_b32_e32 v63, v63, v38, vcc
	v_cmp_eq_u32_e32 vcc, 15, v62
	s_nop 1
	v_cndmask_b32_e32 v62, v63, v39, vcc
	v_add_f32_e32 v61, v61, v62
	v_add_f32_e32 v3, v3, v61
	v_add_u32_e32 v61, 4, v60
	v_cmp_ge_i32_e32 vcc, s6, v61
	s_and_saveexec_b64 s[0:1], vcc
	s_cbranch_execz .LBB0_474
	v_lshlrev_b32_e32 v62, 7, v61
	v_ashrrev_i32_e32 v63, 31, v62
	v_lshl_add_u64 v[62:63], v[62:63], 2, v[52:53]
	v_mov_b32_e32 v62, v218
	v_lshl_or_b32 v63, v61, 9, v2
	s_waitcnt vmcnt(0)
	v_add_f32_e32 v62, v3, v62
	v_mul_f32_e32 v62, 0x3fb8aa3b, v62
	ds_write_b32 v63, v62 offset:32768
; __device__ void attn_item(const Params& p, int l, int b, int h, int qb, char* smem) {
;     ...
;         const int half = tid >> 7, tl = tid & 127;
;         float base = half ? tot[0] : 0.f;
; #pragma unroll
;         for (int jj = 0; jj < 8; ++jj) {
;             const int tile = 2 * jj + half;
;             if (tile <= qb) ckl[tile * 128 + tl] = (base + p.clT[(size_t)bh * 2048 + tile * 128 + tl]) * LOG2E;
;             base += tot[2 * jj + half] + tot[(2 * jj + half + 1) & 15];
;         }
.LBB0_474:
	s_or_b64 exec, exec, s[0:1]
	v_cmp_eq_u32_e32 vcc, 1, v61
	s_nop 1
	v_cndmask_b32_e32 v62, v48, v49, vcc
	v_cmp_eq_u32_e32 vcc, 2, v61
	s_nop 1
	v_cndmask_b32_e32 v62, v62, v50, vcc
	v_cmp_eq_u32_e32 vcc, 3, v61
	s_nop 1
	v_cndmask_b32_e32 v62, v62, v51, vcc
	v_cmp_eq_u32_e32 vcc, 4, v61
	s_nop 1
	v_cndmask_b32_e32 v62, v62, v44, vcc
	v_cmp_eq_u32_e32 vcc, 5, v61
	s_nop 1
	v_cndmask_b32_e32 v62, v62, v45, vcc
	v_cmp_eq_u32_e32 vcc, 6, v61
	s_nop 1
	v_cndmask_b32_e32 v62, v62, v46, vcc
	v_cmp_eq_u32_e32 vcc, 7, v61
	s_nop 1
	v_cndmask_b32_e32 v62, v62, v47, vcc
	v_cmp_eq_u32_e32 vcc, 8, v61
	s_nop 1
	v_cndmask_b32_e32 v62, v62, v40, vcc
	v_cmp_eq_u32_e32 vcc, 9, v61
	s_nop 1
	v_cndmask_b32_e32 v62, v62, v41, vcc
	v_cmp_eq_u32_e32 vcc, 10, v61
	s_nop 1
	v_cndmask_b32_e32 v62, v62, v42, vcc
	v_cmp_eq_u32_e32 vcc, 11, v61
	s_nop 1
	v_cndmask_b32_e32 v62, v62, v43, vcc
	v_cmp_eq_u32_e32 vcc, 12, v61
	s_nop 1
	v_cndmask_b32_e32 v62, v62, v36, vcc
	v_cmp_eq_u32_e32 vcc, 13, v61
	s_nop 1
	v_cndmask_b32_e32 v62, v62, v37, vcc
	v_cmp_eq_u32_e32 vcc, 14, v61
	s_nop 1
	v_cndmask_b32_e32 v62, v62, v38, vcc
	v_cmp_eq_u32_e32 vcc, 15, v61
	s_nop 1
	v_cndmask_b32_e32 v61, v62, v39, vcc
	v_add_u32_e32 v62, 5, v60
	v_and_b32_e32 v62, 15, v62
	v_cmp_eq_u32_e32 vcc, 1, v62
	s_nop 1
	v_cndmask_b32_e32 v63, v48, v49, vcc
	v_cmp_eq_u32_e32 vcc, 2, v62
	s_nop 1
	v_cndmask_b32_e32 v63, v63, v50, vcc
	v_cmp_eq_u32_e32 vcc, 3, v62
	s_nop 1
	v_cndmask_b32_e32 v63, v63, v51, vcc
	v_cmp_eq_u32_e32 vcc, 4, v62
	s_nop 1
	v_cndmask_b32_e32 v63, v63, v44, vcc
	v_cmp_eq_u32_e32 vcc, 5, v62
	s_nop 1
	v_cndmask_b32_e32 v63, v63, v45, vcc
	v_cmp_eq_u32_e32 vcc, 6, v62
	s_nop 1
	v_cndmask_b32_e32 v63, v63, v46, vcc
	v_cmp_eq_u32_e32 vcc, 7, v62
	s_nop 1
	v_cndmask_b32_e32 v63, v63, v47, vcc
	v_cmp_eq_u32_e32 vcc, 8, v62
	s_nop 1
	v_cndmask_b32_e32 v63, v63, v40, vcc
	v_cmp_eq_u32_e32 vcc, 9, v62
	s_nop 1
	v_cndmask_b32_e32 v63, v63, v41, vcc
	v_cmp_eq_u32_e32 vcc, 10, v62
	s_nop 1
	v_cndmask_b32_e32 v63, v63, v42, vcc
	v_cmp_eq_u32_e32 vcc, 11, v62
	s_nop 1
	v_cndmask_b32_e32 v63, v63, v43, vcc
	v_cmp_eq_u32_e32 vcc, 12, v62
	s_nop 1
	v_cndmask_b32_e32 v63, v63, v36, vcc
	v_cmp_eq_u32_e32 vcc, 13, v62
	s_nop 1
	v_cndmask_b32_e32 v63, v63, v37, vcc
	v_cmp_eq_u32_e32 vcc, 14, v62
	s_nop 1
	v_cndmask_b32_e32 v63, v63, v38, vcc
	v_cmp_eq_u32_e32 vcc, 15, v62
	s_nop 1
	v_cndmask_b32_e32 v62, v63, v39, vcc
	v_add_f32_e32 v61, v61, v62
	v_add_f32_e32 v3, v3, v61
	v_add_u32_e32 v61, 6, v60
	v_cmp_ge_i32_e32 vcc, s6, v61
	s_and_saveexec_b64 s[0:1], vcc
	s_cbranch_execz .LBB0_476
	v_lshlrev_b32_e32 v62, 7, v61
	v_ashrrev_i32_e32 v63, 31, v62
	v_lshl_add_u64 v[62:63], v[62:63], 2, v[52:53]
	v_mov_b32_e32 v62, v219
	v_lshl_or_b32 v63, v61, 9, v2
	s_waitcnt vmcnt(0)
	v_add_f32_e32 v62, v3, v62
	v_mul_f32_e32 v62, 0x3fb8aa3b, v62
	ds_write_b32 v63, v62 offset:32768
.LBB0_476:
	s_or_b64 exec, exec, s[0:1]
	v_cmp_eq_u32_e32 vcc, 1, v61
	s_nop 1
	v_cndmask_b32_e32 v62, v48, v49, vcc
	v_cmp_eq_u32_e32 vcc, 2, v61
	s_nop 1
	v_cndmask_b32_e32 v62, v62, v50, vcc
	v_cmp_eq_u32_e32 vcc, 3, v61
	s_nop 1
	v_cndmask_b32_e32 v62, v62, v51, vcc
	v_cmp_eq_u32_e32 vcc, 4, v61
	s_nop 1
	v_cndmask_b32_e32 v62, v62, v44, vcc
	v_cmp_eq_u32_e32 vcc, 5, v61
	s_nop 1
	v_cndmask_b32_e32 v62, v62, v45, vcc
	v_cmp_eq_u32_e32 vcc, 6, v61
	s_nop 1
	v_cndmask_b32_e32 v62, v62, v46, vcc
	v_cmp_eq_u32_e32 vcc, 7, v61
	s_nop 1
	v_cndmask_b32_e32 v62, v62, v47, vcc
	v_cmp_eq_u32_e32 vcc, 8, v61
	s_nop 1
	v_cndmask_b32_e32 v62, v62, v40, vcc
	v_cmp_eq_u32_e32 vcc, 9, v61
	s_nop 1
	v_cndmask_b32_e32 v62, v62, v41, vcc
	v_cmp_eq_u32_e32 vcc, 10, v61
	s_nop 1
	v_cndmask_b32_e32 v62, v62, v42, vcc
	v_cmp_eq_u32_e32 vcc, 11, v61
	s_nop 1
	v_cndmask_b32_e32 v62, v62, v43, vcc
	v_cmp_eq_u32_e32 vcc, 12, v61
	s_nop 1
	v_cndmask_b32_e32 v62, v62, v36, vcc
	v_cmp_eq_u32_e32 vcc, 13, v61
	s_nop 1
	v_cndmask_b32_e32 v62, v62, v37, vcc
	v_cmp_eq_u32_e32 vcc, 14, v61
	s_nop 1
	v_cndmask_b32_e32 v62, v62, v38, vcc
	v_cmp_eq_u32_e32 vcc, 15, v61
	s_nop 1
	v_cndmask_b32_e32 v61, v62, v39, vcc
	v_add_u32_e32 v62, 7, v60
	v_and_b32_e32 v62, 15, v62
	v_cmp_eq_u32_e32 vcc, 1, v62
	s_nop 1
	v_cndmask_b32_e32 v63, v48, v49, vcc
	v_cmp_eq_u32_e32 vcc, 2, v62
	s_nop 1
	v_cndmask_b32_e32 v63, v63, v50, vcc
	v_cmp_eq_u32_e32 vcc, 3, v62
	s_nop 1
	v_cndmask_b32_e32 v63, v63, v51, vcc
	v_cmp_eq_u32_e32 vcc, 4, v62
	s_nop 1
	v_cndmask_b32_e32 v63, v63, v44, vcc
	v_cmp_eq_u32_e32 vcc, 5, v62
	s_nop 1
	v_cndmask_b32_e32 v63, v63, v45, vcc
	v_cmp_eq_u32_e32 vcc, 6, v62
	s_nop 1
	v_cndmask_b32_e32 v63, v63, v46, vcc
	v_cmp_eq_u32_e32 vcc, 7, v62
	s_nop 1
	v_cndmask_b32_e32 v63, v63, v47, vcc
	v_cmp_eq_u32_e32 vcc, 8, v62
	s_nop 1
	v_cndmask_b32_e32 v63, v63, v40, vcc
	v_cmp_eq_u32_e32 vcc, 9, v62
	s_nop 1
	v_cndmask_b32_e32 v63, v63, v41, vcc
	v_cmp_eq_u32_e32 vcc, 10, v62
	s_nop 1
	v_cndmask_b32_e32 v63, v63, v42, vcc
	v_cmp_eq_u32_e32 vcc, 11, v62
	s_nop 1
	v_cndmask_b32_e32 v63, v63, v43, vcc
	v_cmp_eq_u32_e32 vcc, 12, v62
	s_nop 1
	v_cndmask_b32_e32 v63, v63, v36, vcc
	v_cmp_eq_u32_e32 vcc, 13, v62
	s_nop 1
	v_cndmask_b32_e32 v63, v63, v37, vcc
	v_cmp_eq_u32_e32 vcc, 14, v62
	s_nop 1
	v_cndmask_b32_e32 v63, v63, v38, vcc
	v_cmp_eq_u32_e32 vcc, 15, v62
	s_nop 1
	v_cndmask_b32_e32 v62, v63, v39, vcc
	v_add_f32_e32 v61, v61, v62
	v_add_f32_e32 v3, v3, v61
	v_add_u32_e32 v61, 8, v60
	v_cmp_ge_i32_e32 vcc, s6, v61
	s_and_saveexec_b64 s[0:1], vcc
	s_cbranch_execz .LBB0_478
	v_lshlrev_b32_e32 v62, 7, v61
	v_ashrrev_i32_e32 v63, 31, v62
	v_lshl_add_u64 v[62:63], v[62:63], 2, v[52:53]
	v_mov_b32_e32 v62, v220
	v_lshl_or_b32 v63, v61, 9, v2
	s_waitcnt vmcnt(0)
	v_add_f32_e32 v62, v3, v62
	v_mul_f32_e32 v62, 0x3fb8aa3b, v62
	ds_write_b32 v63, v62 offset:32768
; __device__ void attn_item(const Params& p, int l, int b, int h, int qb, char* smem) {
;     ...
;         const int half = tid >> 7, tl = tid & 127;
;         float base = half ? tot[0] : 0.f;
; #pragma unroll
;         for (int jj = 0; jj < 8; ++jj) {
;             const int tile = 2 * jj + half;
;             if (tile <= qb) ckl[tile * 128 + tl] = (base + p.clT[(size_t)bh * 2048 + tile * 128 + tl]) * LOG2E;
;             base += tot[2 * jj + half] + tot[(2 * jj + half + 1) & 15];
;         }
.LBB0_478:
	s_or_b64 exec, exec, s[0:1]
	v_cmp_eq_u32_e32 vcc, 1, v61
	s_nop 1
	v_cndmask_b32_e32 v62, v48, v49, vcc
	v_cmp_eq_u32_e32 vcc, 2, v61
	s_nop 1
	v_cndmask_b32_e32 v62, v62, v50, vcc
	v_cmp_eq_u32_e32 vcc, 3, v61
	s_nop 1
	v_cndmask_b32_e32 v62, v62, v51, vcc
	v_cmp_eq_u32_e32 vcc, 4, v61
	s_nop 1
	v_cndmask_b32_e32 v62, v62, v44, vcc
	v_cmp_eq_u32_e32 vcc, 5, v61
	s_nop 1
	v_cndmask_b32_e32 v62, v62, v45, vcc
	v_cmp_eq_u32_e32 vcc, 6, v61
	s_nop 1
	v_cndmask_b32_e32 v62, v62, v46, vcc
	v_cmp_eq_u32_e32 vcc, 7, v61
	s_nop 1
	v_cndmask_b32_e32 v62, v62, v47, vcc
	v_cmp_eq_u32_e32 vcc, 8, v61
	s_nop 1
	v_cndmask_b32_e32 v62, v62, v40, vcc
	v_cmp_eq_u32_e32 vcc, 9, v61
	s_nop 1
	v_cndmask_b32_e32 v62, v62, v41, vcc
	v_cmp_eq_u32_e32 vcc, 10, v61
	s_nop 1
	v_cndmask_b32_e32 v62, v62, v42, vcc
	v_cmp_eq_u32_e32 vcc, 11, v61
	s_nop 1
	v_cndmask_b32_e32 v62, v62, v43, vcc
	v_cmp_eq_u32_e32 vcc, 12, v61
	s_nop 1
	v_cndmask_b32_e32 v62, v62, v36, vcc
	v_cmp_eq_u32_e32 vcc, 13, v61
	s_nop 1
	v_cndmask_b32_e32 v62, v62, v37, vcc
	v_cmp_eq_u32_e32 vcc, 14, v61
	s_nop 1
	v_cndmask_b32_e32 v62, v62, v38, vcc
	v_cmp_eq_u32_e32 vcc, 15, v61
	s_nop 1
	v_cndmask_b32_e32 v61, v62, v39, vcc
	v_add_u32_e32 v62, 9, v60
	v_and_b32_e32 v62, 15, v62
	v_cmp_eq_u32_e32 vcc, 1, v62
	s_nop 1
	v_cndmask_b32_e32 v63, v48, v49, vcc
	v_cmp_eq_u32_e32 vcc, 2, v62
	s_nop 1
	v_cndmask_b32_e32 v63, v63, v50, vcc
	v_cmp_eq_u32_e32 vcc, 3, v62
	s_nop 1
	v_cndmask_b32_e32 v63, v63, v51, vcc
	v_cmp_eq_u32_e32 vcc, 4, v62
	s_nop 1
	v_cndmask_b32_e32 v63, v63, v44, vcc
	v_cmp_eq_u32_e32 vcc, 5, v62
	s_nop 1
	v_cndmask_b32_e32 v63, v63, v45, vcc
	v_cmp_eq_u32_e32 vcc, 6, v62
	s_nop 1
	v_cndmask_b32_e32 v63, v63, v46, vcc
	v_cmp_eq_u32_e32 vcc, 7, v62
	s_nop 1
	v_cndmask_b32_e32 v63, v63, v47, vcc
	v_cmp_eq_u32_e32 vcc, 8, v62
	s_nop 1
	v_cndmask_b32_e32 v63, v63, v40, vcc
	v_cmp_eq_u32_e32 vcc, 9, v62
	s_nop 1
	v_cndmask_b32_e32 v63, v63, v41, vcc
	v_cmp_eq_u32_e32 vcc, 10, v62
	s_nop 1
	v_cndmask_b32_e32 v63, v63, v42, vcc
	v_cmp_eq_u32_e32 vcc, 11, v62
	s_nop 1
	v_cndmask_b32_e32 v63, v63, v43, vcc
	v_cmp_eq_u32_e32 vcc, 12, v62
	s_nop 1
	v_cndmask_b32_e32 v63, v63, v36, vcc
	v_cmp_eq_u32_e32 vcc, 13, v62
	s_nop 1
	v_cndmask_b32_e32 v63, v63, v37, vcc
	v_cmp_eq_u32_e32 vcc, 14, v62
	s_nop 1
	v_cndmask_b32_e32 v63, v63, v38, vcc
	v_cmp_eq_u32_e32 vcc, 15, v62
	s_nop 1
	v_cndmask_b32_e32 v62, v63, v39, vcc
	v_add_f32_e32 v61, v61, v62
	v_add_f32_e32 v3, v3, v61
	v_add_u32_e32 v61, 10, v60
	v_cmp_ge_i32_e32 vcc, s6, v61
	s_and_saveexec_b64 s[0:1], vcc
	s_cbranch_execz .LBB0_480
	v_lshlrev_b32_e32 v62, 7, v61
	v_ashrrev_i32_e32 v63, 31, v62
	v_lshl_add_u64 v[62:63], v[62:63], 2, v[52:53]
	v_mov_b32_e32 v62, v221
	v_lshl_or_b32 v63, v61, 9, v2
	s_waitcnt vmcnt(0)
	v_add_f32_e32 v62, v3, v62
	v_mul_f32_e32 v62, 0x3fb8aa3b, v62
	ds_write_b32 v63, v62 offset:32768
; __device__ void attn_item(const Params& p, int l, int b, int h, int qb, char* smem) {
;     ...
;         const int half = tid >> 7, tl = tid & 127;
;         float base = half ? tot[0] : 0.f;
; #pragma unroll
;         for (int jj = 0; jj < 8; ++jj) {
;             const int tile = 2 * jj + half;
;             if (tile <= qb) ckl[tile * 128 + tl] = (base + p.clT[(size_t)bh * 2048 + tile * 128 + tl]) * LOG2E;
;             base += tot[2 * jj + half] + tot[(2 * jj + half + 1) & 15];
;         }
.LBB0_480:
	s_or_b64 exec, exec, s[0:1]
	v_cmp_eq_u32_e32 vcc, 1, v61
	s_nop 1
	v_cndmask_b32_e32 v62, v48, v49, vcc
	v_cmp_eq_u32_e32 vcc, 2, v61
	s_nop 1
	v_cndmask_b32_e32 v62, v62, v50, vcc
	v_cmp_eq_u32_e32 vcc, 3, v61
	s_nop 1
	v_cndmask_b32_e32 v62, v62, v51, vcc
	v_cmp_eq_u32_e32 vcc, 4, v61
	s_nop 1
	v_cndmask_b32_e32 v62, v62, v44, vcc
	v_cmp_eq_u32_e32 vcc, 5, v61
	s_nop 1
	v_cndmask_b32_e32 v62, v62, v45, vcc
	v_cmp_eq_u32_e32 vcc, 6, v61
	s_nop 1
	v_cndmask_b32_e32 v62, v62, v46, vcc
	v_cmp_eq_u32_e32 vcc, 7, v61
	s_nop 1
	v_cndmask_b32_e32 v62, v62, v47, vcc
	v_cmp_eq_u32_e32 vcc, 8, v61
	s_nop 1
	v_cndmask_b32_e32 v62, v62, v40, vcc
	v_cmp_eq_u32_e32 vcc, 9, v61
	s_nop 1
	v_cndmask_b32_e32 v62, v62, v41, vcc
	v_cmp_eq_u32_e32 vcc, 10, v61
	s_nop 1
	v_cndmask_b32_e32 v62, v62, v42, vcc
	v_cmp_eq_u32_e32 vcc, 11, v61
	s_nop 1
	v_cndmask_b32_e32 v62, v62, v43, vcc
	v_cmp_eq_u32_e32 vcc, 12, v61
	s_nop 1
	v_cndmask_b32_e32 v62, v62, v36, vcc
	v_cmp_eq_u32_e32 vcc, 13, v61
	s_nop 1
	v_cndmask_b32_e32 v62, v62, v37, vcc
	v_cmp_eq_u32_e32 vcc, 14, v61
	s_nop 1
	v_cndmask_b32_e32 v62, v62, v38, vcc
	v_cmp_eq_u32_e32 vcc, 15, v61
	s_nop 1
	v_cndmask_b32_e32 v61, v62, v39, vcc
	v_add_u32_e32 v62, 11, v60
	v_and_b32_e32 v62, 15, v62
	v_cmp_eq_u32_e32 vcc, 1, v62
	s_nop 1
	v_cndmask_b32_e32 v63, v48, v49, vcc
	v_cmp_eq_u32_e32 vcc, 2, v62
	s_nop 1
	v_cndmask_b32_e32 v63, v63, v50, vcc
	v_cmp_eq_u32_e32 vcc, 3, v62
	s_nop 1
	v_cndmask_b32_e32 v63, v63, v51, vcc
	v_cmp_eq_u32_e32 vcc, 4, v62
	s_nop 1
	v_cndmask_b32_e32 v63, v63, v44, vcc
	v_cmp_eq_u32_e32 vcc, 5, v62
	s_nop 1
	v_cndmask_b32_e32 v63, v63, v45, vcc
	v_cmp_eq_u32_e32 vcc, 6, v62
	s_nop 1
	v_cndmask_b32_e32 v63, v63, v46, vcc
	v_cmp_eq_u32_e32 vcc, 7, v62
	s_nop 1
	v_cndmask_b32_e32 v63, v63, v47, vcc
	v_cmp_eq_u32_e32 vcc, 8, v62
	s_nop 1
	v_cndmask_b32_e32 v63, v63, v40, vcc
	v_cmp_eq_u32_e32 vcc, 9, v62
	s_nop 1
	v_cndmask_b32_e32 v63, v63, v41, vcc
	v_cmp_eq_u32_e32 vcc, 10, v62
	s_nop 1
	v_cndmask_b32_e32 v63, v63, v42, vcc
	v_cmp_eq_u32_e32 vcc, 11, v62
	s_nop 1
	v_cndmask_b32_e32 v63, v63, v43, vcc
	v_cmp_eq_u32_e32 vcc, 12, v62
	s_nop 1
	v_cndmask_b32_e32 v63, v63, v36, vcc
	v_cmp_eq_u32_e32 vcc, 13, v62
	s_nop 1
	v_cndmask_b32_e32 v63, v63, v37, vcc
	v_cmp_eq_u32_e32 vcc, 14, v62
	s_nop 1
	v_cndmask_b32_e32 v63, v63, v38, vcc
	v_cmp_eq_u32_e32 vcc, 15, v62
	s_nop 1
	v_cndmask_b32_e32 v62, v63, v39, vcc
	v_add_f32_e32 v61, v61, v62
	v_add_u32_e32 v62, 12, v60
	v_add_f32_e32 v61, v3, v61
	v_cmp_ge_i32_e32 vcc, s6, v62
	s_and_saveexec_b64 s[0:1], vcc
	s_cbranch_execz .LBB0_482
	v_lshlrev_b32_e32 v64, 7, v62
	v_ashrrev_i32_e32 v65, 31, v64
	v_lshl_add_u64 v[64:65], v[64:65], 2, v[52:53]
	v_mov_b32_e32 v3, v222
	v_lshl_or_b32 v63, v62, 9, v2
	s_waitcnt vmcnt(0)
	v_add_f32_e32 v3, v61, v3
	v_mul_f32_e32 v3, 0x3fb8aa3b, v3
	ds_write_b32 v63, v3 offset:32768
.LBB0_482:
	s_or_b64 exec, exec, s[0:1]
	v_add_u32_e32 v3, 14, v60
	v_cmp_ge_i32_e32 vcc, s6, v3
	s_and_saveexec_b64 s[0:1], vcc
	s_cbranch_execz .LBB0_484
	v_cmp_eq_u32_e32 vcc, 1, v62
	v_add_u32_e32 v60, 13, v60
	v_and_b32_e32 v60, 15, v60
	v_cndmask_b32_e32 v63, v48, v49, vcc
	v_cmp_eq_u32_e32 vcc, 2, v62
	v_lshl_or_b32 v2, v3, 9, v2
	s_nop 0
	v_cndmask_b32_e32 v63, v63, v50, vcc
	v_cmp_eq_u32_e32 vcc, 3, v62
	s_nop 1
	v_cndmask_b32_e32 v63, v63, v51, vcc
	v_cmp_eq_u32_e32 vcc, 4, v62
	s_nop 1
	v_cndmask_b32_e32 v63, v63, v44, vcc
	v_cmp_eq_u32_e32 vcc, 5, v62
	s_nop 1
	v_cndmask_b32_e32 v63, v63, v45, vcc
	v_cmp_eq_u32_e32 vcc, 6, v62
	s_nop 1
	v_cndmask_b32_e32 v63, v63, v46, vcc
	v_cmp_eq_u32_e32 vcc, 7, v62
	s_nop 1
	v_cndmask_b32_e32 v63, v63, v47, vcc
	v_cmp_eq_u32_e32 vcc, 8, v62
	s_nop 1
	v_cndmask_b32_e32 v63, v63, v40, vcc
	v_cmp_eq_u32_e32 vcc, 9, v62
	s_nop 1
	v_cndmask_b32_e32 v63, v63, v41, vcc
	v_cmp_eq_u32_e32 vcc, 10, v62
	s_nop 1
	v_cndmask_b32_e32 v63, v63, v42, vcc
	v_cmp_eq_u32_e32 vcc, 11, v62
	s_nop 1
	v_cndmask_b32_e32 v63, v63, v43, vcc
	v_cmp_eq_u32_e32 vcc, 12, v62
	s_nop 1
	v_cndmask_b32_e32 v63, v63, v36, vcc
	v_cmp_eq_u32_e32 vcc, 13, v62
	s_nop 1
	v_cndmask_b32_e32 v63, v63, v37, vcc
	v_cmp_eq_u32_e32 vcc, 14, v62
	s_nop 1
	v_cndmask_b32_e32 v63, v63, v38, vcc
	v_cmp_eq_u32_e32 vcc, 15, v62
	s_nop 1
	v_cndmask_b32_e32 v62, v63, v39, vcc
	v_cmp_eq_u32_e32 vcc, 1, v60
	s_nop 1
	v_cndmask_b32_e32 v48, v48, v49, vcc
	v_cmp_eq_u32_e32 vcc, 2, v60
	s_nop 1
	v_cndmask_b32_e32 v48, v48, v50, vcc
	v_cmp_eq_u32_e32 vcc, 3, v60
	s_nop 1
	v_cndmask_b32_e32 v48, v48, v51, vcc
	v_cmp_eq_u32_e32 vcc, 4, v60
	s_nop 1
	v_cndmask_b32_e32 v44, v48, v44, vcc
	v_cmp_eq_u32_e32 vcc, 5, v60
	s_nop 1
	v_cndmask_b32_e32 v44, v44, v45, vcc
	v_cmp_eq_u32_e32 vcc, 6, v60
	s_nop 1
	v_cndmask_b32_e32 v44, v44, v46, vcc
	v_cmp_eq_u32_e32 vcc, 7, v60
	s_nop 1
	v_cndmask_b32_e32 v44, v44, v47, vcc
	v_cmp_eq_u32_e32 vcc, 8, v60
	s_nop 1
	v_cndmask_b32_e32 v40, v44, v40, vcc
	v_cmp_eq_u32_e32 vcc, 9, v60
	s_nop 1
	v_cndmask_b32_e32 v40, v40, v41, vcc
	v_cmp_eq_u32_e32 vcc, 10, v60
	s_nop 1
	v_cndmask_b32_e32 v40, v40, v42, vcc
	v_cmp_eq_u32_e32 vcc, 11, v60
	s_nop 1
	v_cndmask_b32_e32 v40, v40, v43, vcc
	v_cmp_eq_u32_e32 vcc, 12, v60
	s_nop 1
	v_cndmask_b32_e32 v36, v40, v36, vcc
	v_cmp_eq_u32_e32 vcc, 13, v60
	s_nop 1
	v_cndmask_b32_e32 v36, v36, v37, vcc
	v_cmp_eq_u32_e32 vcc, 14, v60
	s_nop 1
	v_cndmask_b32_e32 v36, v36, v38, vcc
	v_cmp_eq_u32_e32 vcc, 15, v60
	s_nop 1
	v_cndmask_b32_e32 v36, v36, v39, vcc
	v_add_f32_e32 v36, v62, v36
	v_add_f32_e32 v38, v61, v36
	v_lshlrev_b32_e32 v36, 7, v3
	v_ashrrev_i32_e32 v37, 31, v36
	v_lshl_add_u64 v[36:37], v[36:37], 2, v[52:53]
	v_mov_b32_e32 v36, v223
	s_waitcnt vmcnt(0)
	v_add_f32_e32 v36, v36, v38
	v_mul_f32_e32 v36, 0x3fb8aa3b, v36
	ds_write_b32 v2, v36 offset:32768
